# v12: MoBA softmax scale folded into q (before its single bf16 rounding) and shift folded into the QK accumulator init
# speedup vs baseline: 1.0202x; 1.0197x over previous
; #define MW_DMA_BLK(blkidx, buf) do { _Pragma("unroll") for (int z_ = 0; z_ < 8; ++z_) \
;             __builtin_amdgcn_global_load_lds((const unsigned*)(gsrc + (size_t)((blkidx) * 8 + z_) * 4096), (LAS unsigned*)(lds + (unsigned)(buf) * 65536u + (unsigned)z_ * 8192u + wpiece), 16, 0, 0); } while (0)
; DI void rope_q(bf16x8 (&qf)[4], const float* gq, int pos, int hi, int x32) {
;     ...
;     for (int kk = 0; kk < 4; ++kk) { const f32x4 g0 = *(const f32x4*)(gq + 16 * kk + 8 * hi), g1 = *(const f32x4*)(gq + 16 * kk + 8 * hi + 4);
; #pragma unroll
;         for (int j = 0; j < 4; ++j) { v[kk][j] = v[kk][j] * rstd * g0[j]; v[kk][4 + j] = v[kk][4 + j] * rstd * g1[j]; } }
; #pragma unroll
;     for (int kk = 0; kk < 2; ++kk)
; #pragma unroll
;         for (int j = 0; j < 8; ++j) {
;             const float invf = exp2f(-(float)(16 * kk + 8 * hi + j) * (13.287712379549449f / 32.f));
;             float r = (float)pos * invf * 0.15915494309189535f; r = r - floorf(r);
; DI void moba_wg_phase(const bf16* qb, const unsigned char* kfb, const unsigned char* vfb, bf16* ob, const bf16* kmean, const float* gains, int G, LAS unsigned char* lds, const int wave_s) {
;     ...
;         const int hi = lane_u >> 5, col = lane_u & 31, xq = (lane_u ^ 32) << 2; const unsigned lofs = (unsigned)lane_u * 16u;
;         const int it = v / per, own = (v + it) & 15, bh = xx * (128 / nx) + (v >> 4), b = bh >> 4, h = bh & 15;
;         const int tok0 = b * SEQ, q0 = own * 256 + 32 * wave, tq = q0 + col;
;         const char* gsrc = (const char*)((wave < 4) ? kfb : vfb) + ((size_t)((b * 16 + h) * 128) << 12) + (unsigned)(wave & 3) * 1024u + lofs;
;         const int nt = 8 * own + 8;
;     ...
;         MW_DMA_BLK(0, 0);
;         bf16x8 qf[4];
;         { const bf16* qp = qb + (size_t)(tok0 + tq) * 1024 + h * 64 + 8 * hi;
; #pragma unroll
;           for (int kk = 0; kk < 4; ++kk) qf[kk] = *(const bf16x8*)(qp + 16 * kk); }
;         rope_q(qf, gains, tq, hi, xq);
.LBB0_496:
	s_ashr_i32 s4, s94, 31
	v_readlane_b32 s5, v242, 38
	s_xor_b32 s8, s4, s5
	s_abs_i32 s4, s94
	v_readlane_b32 s5, v242, 39
	s_mul_hi_u32 s5, s4, s5
	s_mul_i32 s6, s5, s52
	s_sub_i32 s4, s4, s6
	s_add_i32 s6, s5, 1
	s_sub_i32 s7, s4, s52
	s_cmp_ge_u32 s4, s52
	s_cselect_b32 s5, s6, s5
	s_cselect_b32 s4, s7, s4
	s_add_i32 s6, s5, 1
	s_cmp_ge_u32 s4, s52
	s_cselect_b32 s4, s6, s5
	s_xor_b32 s11, s4, s8
	s_sub_i32 s9, s11, s8
	s_lshr_b32 s4, s9, 1
	s_add_i32 s4, s4, s94
	s_and_b32 s95, s4, 15
	s_and_b32 s4, s9, 1
	s_mul_i32 s4, s4, 15
	s_xor_b32 s95, s95, s4
	s_ashr_i32 s4, s94, 4
	v_readlane_b32 s5, v242, 10
	s_add_i32 s6, s4, s5
	s_and_b32 s12, s4, 15
	s_lshl_b32 s10, s95, 8
	v_readlane_b32 s4, v242, 11
	s_add_i32 s10, s10, s4
	s_lshl_b32 s4, s6, 7
	s_ashr_i32 s5, s4, 31
	s_lshl_b64 s[4:5], s[4:5], 12
	v_mov_b32_e32 v104, v98
	s_add_u32 s4, s65, s4
	s_addc_u32 s5, s88, s5
	v_lshlrev_b32_e32 v0, 4, v104
	s_mov_b32 m0, s66
	v_lshl_add_u64 v[100:101], s[4:5], 0, v[0:1]
	v_ashrrev_i32_e32 v105, 5, v104
	global_load_lds_dwordx4 v0, s[4:5]
	v_lshl_add_u64 v[2:3], v[100:101], 0, s[72:73]
	s_add_i32 m0, s66, 0x2000
	s_mov_b64 s[4:5], 0x2000
	global_load_lds_dwordx4 v[2:3], off
	v_lshl_add_u64 v[2:3], v[100:101], 0, s[4:5]
	s_add_i32 m0, s66, 0x4000
	s_mov_b64 s[4:5], 0x3000
	v_lshlrev_b32_e32 v52, 3, v105
	global_load_lds_dwordx4 v[2:3], off
	v_lshl_add_u64 v[2:3], v[100:101], 0, s[4:5]
	s_add_i32 m0, s66, 0x6000
	s_mov_b64 s[4:5], 0x4000
	v_cvt_f32_i32_e32 v20, v52
	global_load_lds_dwordx4 v[2:3], off
	v_lshl_add_u64 v[2:3], v[100:101], 0, s[4:5]
	s_add_i32 m0, s66, 0x8000
	s_mov_b64 s[4:5], 0x5000
	global_load_lds_dwordx4 v[2:3], off
	v_lshl_add_u64 v[2:3], v[100:101], 0, s[4:5]
	s_add_i32 m0, s66, 0xa000
	s_mov_b64 s[4:5], 0x6000
	global_load_lds_dwordx4 v[2:3], off
	v_lshl_add_u64 v[2:3], v[100:101], 0, s[4:5]
	s_add_i32 m0, s66, 0xc000
	s_mov_b64 s[4:5], 0x7000
	global_load_lds_dwordx4 v[2:3], off
	v_lshl_add_u64 v[2:3], v[100:101], 0, s[4:5]
	s_ashr_i32 s4, s6, 4
	v_and_or_b32 v107, v104, 31, s10
	v_mul_f32_e32 v21, 0xbed49a78, v20
	v_lshl_add_u32 v50, s4, 12, v107
	v_cmp_gt_f32_e32 vcc, s91, v21
	s_add_i32 m0, s66, 0xe000
	v_ashrrev_i32_e32 v51, 31, v50
	v_cndmask_b32_e32 v21, 0, v206, vcc
	global_load_lds_dwordx4 v[2:3], off
	v_lshlrev_b64 v[2:3], 11, v[50:51]
	v_fmac_f32_e32 v21, 0xbed49a78, v20
	v_lshl_add_u64 v[2:3], s[40:41], 0, v[2:3]
	s_lshl_b32 s68, s12, 7
	v_exp_f32_e32 v54, v21
	v_lshl_add_u64 v[2:3], v[2:3], 0, s[68:69]
	v_ashrrev_i32_e32 v53, 31, v52
	v_lshl_add_u64 v[2:3], v[52:53], 1, v[2:3]
	v_lshl_add_u64 v[18:19], v[52:53], 2, s[38:39]
	v_cvt_f32_u32_e32 v53, v107
	v_cndmask_b32_e32 v55, 0, v207, vcc
	v_ldexp_f32 v54, v54, v55
	v_or_b32_e32 v55, 1, v52
	v_cvt_f32_i32_e32 v55, v55
	v_mul_f32_e32 v54, v54, v53
	v_mul_f32_e32 v56, 0.15915494, v54
	v_floor_f32_e32 v56, v56
	v_fma_f32 v54, v54, 0.15915494, -v56
	v_mul_f32_e32 v56, 0xbed49a78, v55
	v_cmp_gt_f32_e32 vcc, s91, v56
	global_load_dwordx4 v[38:41], v[2:3], off
	global_load_dwordx4 v[46:49], v[2:3], off offset:32
	global_load_dwordx4 v[34:37], v[2:3], off offset:64
	global_load_dwordx4 v[42:45], v[2:3], off offset:96
	v_cndmask_b32_e32 v56, 0, v206, vcc
	v_fmac_f32_e32 v56, 0xbed49a78, v55
	v_exp_f32_e32 v55, v56
	v_cndmask_b32_e32 v57, 0, v207, vcc
	v_lshlrev_b32_e32 v4, 2, v104
	v_xor_b32_e32 v106, 0x80, v4
	v_ldexp_f32 v55, v55, v57
	v_or_b32_e32 v57, 2, v52
	v_cvt_f32_i32_e32 v57, v57
	v_mul_f32_e32 v55, v55, v53
	v_mul_f32_e32 v58, 0.15915494, v55
	v_floor_f32_e32 v58, v58
	v_fma_f32 v55, v55, 0.15915494, -v58
	v_mul_f32_e32 v58, 0xbed49a78, v57
	v_cmp_gt_f32_e32 vcc, s91, v58
	global_load_dwordx4 v[30:33], v[18:19], off
	global_load_dwordx4 v[26:29], v[18:19], off offset:16
	global_load_dwordx4 v[10:13], v[18:19], off offset:64
	global_load_dwordx4 v[2:5], v[18:19], off offset:80
	v_cndmask_b32_e32 v58, 0, v206, vcc
	v_fmac_f32_e32 v58, 0xbed49a78, v57
	v_exp_f32_e32 v58, v58
	v_cndmask_b32_e32 v59, 0, v207, vcc
	s_lshl_b32 s4, s4, 8
	s_lshl_b32 s5, s12, 4
	v_ldexp_f32 v58, v58, v59
	v_or_b32_e32 v59, 3, v52
	v_cvt_f32_i32_e32 v59, v59
	v_mul_f32_e32 v58, v58, v53
	v_mul_f32_e32 v60, 0.15915494, v58
	v_floor_f32_e32 v60, v60
	v_fma_f32 v58, v58, 0.15915494, -v60
	v_mul_f32_e32 v60, 0xbed49a78, v59
	v_cmp_gt_f32_e32 vcc, s91, v60
	global_load_dwordx4 v[14:17], v[18:19], off offset:128
	global_load_dwordx4 v[6:9], v[18:19], off offset:144
	v_cndmask_b32_e32 v60, 0, v206, vcc
	v_fmac_f32_e32 v60, 0xbed49a78, v59
	v_exp_f32_e32 v59, v60
	v_cndmask_b32_e32 v61, 0, v207, vcc
	global_load_dwordx4 v[22:25], v[18:19], off offset:192
	s_nop 0
	global_load_dwordx4 v[18:21], v[18:19], off offset:208
	s_or_b32 s4, s4, s5
	v_ldexp_f32 v59, v59, v61
	v_or_b32_e32 v61, 4, v52
	v_cvt_f32_i32_e32 v61, v61
	v_mul_f32_e32 v59, v59, v53
	v_mul_f32_e32 v62, 0.15915494, v59
	v_floor_f32_e32 v62, v62
	v_fma_f32 v59, v59, 0.15915494, -v62
	v_mul_f32_e32 v62, 0xbed49a78, v61
	v_cmp_gt_f32_e32 vcc, s91, v62
	s_ashr_i32 s5, s4, 31
	s_lshl_b64 s[4:5], s[4:5], 7
	v_cndmask_b32_e32 v62, 0, v206, vcc
	v_fmac_f32_e32 v62, 0xbed49a78, v61
	v_exp_f32_e32 v62, v62
	v_cndmask_b32_e32 v63, 0, v207, vcc
	s_add_u32 s4, s44, s4
	s_addc_u32 s5, s54, s5
	v_ldexp_f32 v62, v62, v63
	v_or_b32_e32 v63, 5, v52
	v_cvt_f32_i32_e32 v63, v63
	v_mul_f32_e32 v62, v62, v53
	v_mul_f32_e32 v64, 0.15915494, v62
	v_floor_f32_e32 v64, v64
	v_fma_f32 v62, v62, 0.15915494, -v64
	v_mul_f32_e32 v64, 0xbed49a78, v63
	v_cmp_gt_f32_e32 vcc, s91, v64
	v_cos_f32_e32 v56, v54
	v_sin_f32_e32 v54, v54
	v_cndmask_b32_e32 v64, 0, v206, vcc
	v_fmac_f32_e32 v64, 0xbed49a78, v63
	v_exp_f32_e32 v63, v64
	v_cndmask_b32_e32 v65, 0, v207, vcc
	v_cos_f32_e32 v57, v55
	v_sin_f32_e32 v55, v55
	v_ldexp_f32 v63, v63, v65
	v_or_b32_e32 v65, 6, v52
	v_cvt_f32_i32_e32 v65, v65
	v_mul_f32_e32 v63, v63, v53
	v_mul_f32_e32 v66, 0.15915494, v63
	v_floor_f32_e32 v66, v66
	v_fma_f32 v63, v63, 0.15915494, -v66
	v_mul_f32_e32 v66, 0xbed49a78, v65
	v_cmp_gt_f32_e32 vcc, s91, v66
	s_waitcnt vmcnt(0)
; DI float bperm(float v, int x32) { return __builtin_bit_cast(float, __builtin_amdgcn_ds_bpermute(x32, __builtin_bit_cast(int, v))); }
; DI void rope_q(bf16x8 (&qf)[4], const float* gq, int pos, int hi, int x32) {
;     float v[4][8]; float ss = 0.f;
; #pragma unroll
;     for (int kk = 0; kk < 4; ++kk) { const v4u raw = __builtin_bit_cast(v4u, qf[kk]);
; #pragma unroll
;         for (int t = 0; t < 4; ++t) { v[kk][2 * t] = __builtin_bit_cast(float, raw[t] << 16); v[kk][2 * t + 1] = __builtin_bit_cast(float, raw[t] & 0xffff0000u); } }
; #pragma unroll
;     for (int kk = 0; kk < 4; ++kk)
; #pragma unroll
;         for (int j = 0; j < 8; ++j) ss += v[kk][j] * v[kk][j];
;     ss += bperm(ss, x32);
;     const float rstd = rsqrtf(ss * (1.f / 64.f) + EPS);
; #pragma unroll
;     for (int kk = 0; kk < 4; ++kk) { const f32x4 g0 = *(const f32x4*)(gq + 16 * kk + 8 * hi), g1 = *(const f32x4*)(gq + 16 * kk + 8 * hi + 4);
; #pragma unroll
;         for (int j = 0; j < 4; ++j) { v[kk][j] = v[kk][j] * rstd * g0[j]; v[kk][4 + j] = v[kk][4 + j] * rstd * g1[j]; } }
; #pragma unroll
;     for (int kk = 0; kk < 2; ++kk)
; #pragma unroll
;         for (int j = 0; j < 8; ++j) {
;             const float invf = exp2f(-(float)(16 * kk + 8 * hi + j) * (13.287712379549449f / 32.f));
;             float r = (float)pos * invf * 0.15915494309189535f; r = r - floorf(r);
	v_lshlrev_b32_e32 v138, 16, v38
	v_and_b32_e32 v139, 0xffff0000, v38
	v_cndmask_b32_e32 v66, 0, v206, vcc
	v_fmac_f32_e32 v66, 0xbed49a78, v65
	v_exp_f32_e32 v66, v66
	v_cndmask_b32_e32 v67, 0, v207, vcc
	v_lshlrev_b32_e32 v130, 16, v39
	v_and_b32_e32 v131, 0xffff0000, v39
	v_ldexp_f32 v66, v66, v67
	v_or_b32_e32 v67, 7, v52
	v_cvt_f32_i32_e32 v67, v67
	v_mul_f32_e32 v66, v66, v53
	v_mul_f32_e32 v68, 0.15915494, v66
	v_floor_f32_e32 v68, v68
	v_fma_f32 v66, v66, 0.15915494, -v68
	v_mul_f32_e32 v68, 0xbed49a78, v67
	v_cmp_gt_f32_e32 vcc, s91, v68
	v_lshlrev_b32_e32 v132, 16, v35
	v_and_b32_e32 v133, 0xffff0000, v35
	v_cndmask_b32_e32 v68, 0, v206, vcc
	v_fmac_f32_e32 v68, 0xbed49a78, v67
	v_exp_f32_e32 v67, v68
	v_cndmask_b32_e32 v69, 0, v207, vcc
	v_lshlrev_b32_e32 v38, 16, v34
	v_and_b32_e32 v39, 0xffff0000, v34
	v_ldexp_f32 v67, v67, v69
	v_add_u32_e32 v69, 16, v52
	v_cvt_f32_i32_e32 v69, v69
	v_mul_f32_e32 v67, v67, v53
	v_mul_f32_e32 v70, 0.15915494, v67
	v_floor_f32_e32 v70, v70
	v_fma_f32 v67, v67, 0.15915494, -v70
	v_mul_f32_e32 v70, 0xbed49a78, v69
	v_cmp_gt_f32_e32 vcc, s91, v70
	v_pk_mul_f32 v[34:35], v[138:139], v[138:139]
	v_pk_mul_f32 v[134:135], v[130:131], v[130:131]
	v_cndmask_b32_e32 v70, 0, v206, vcc
	v_fmac_f32_e32 v70, 0xbed49a78, v69
	v_exp_f32_e32 v70, v70
	v_cndmask_b32_e32 v71, 0, v207, vcc
	v_add_f32_e32 v34, v34, v35
	v_lshlrev_b32_e32 v126, 16, v40
	v_ldexp_f32 v70, v70, v71
	v_add_u32_e32 v71, 17, v52
	v_cvt_f32_i32_e32 v71, v71
	v_mul_f32_e32 v70, v70, v53
	v_mul_f32_e32 v72, 0.15915494, v70
	v_floor_f32_e32 v72, v72
	v_fma_f32 v70, v70, 0.15915494, -v72
	v_mul_f32_e32 v72, 0xbed49a78, v71
	v_cmp_gt_f32_e32 vcc, s91, v72
	v_and_b32_e32 v127, 0xffff0000, v40
	v_add_f32_e32 v34, v134, v34
	v_cndmask_b32_e32 v72, 0, v206, vcc
	v_fmac_f32_e32 v72, 0xbed49a78, v71
	v_exp_f32_e32 v71, v72
	v_cndmask_b32_e32 v73, 0, v207, vcc
	v_lshlrev_b32_e32 v88, 16, v49
	v_and_b32_e32 v89, 0xffff0000, v49
	v_ldexp_f32 v71, v71, v73
	v_add_u32_e32 v73, 18, v52
	v_cvt_f32_i32_e32 v73, v73
	v_mul_f32_e32 v71, v71, v53
	v_mul_f32_e32 v74, 0.15915494, v71
	v_floor_f32_e32 v74, v74
	v_fma_f32 v71, v71, 0.15915494, -v74
	v_mul_f32_e32 v74, 0xbed49a78, v73
	v_cmp_gt_f32_e32 vcc, s91, v74
	v_lshlrev_b32_e32 v86, 16, v45
	v_and_b32_e32 v87, 0xffff0000, v45
	v_cndmask_b32_e32 v74, 0, v206, vcc
	v_fmac_f32_e32 v74, 0xbed49a78, v73
	v_exp_f32_e32 v74, v74
	v_cndmask_b32_e32 v75, 0, v207, vcc
	v_lshlrev_b32_e32 v90, 16, v48
	v_and_b32_e32 v91, 0xffff0000, v48
	v_ldexp_f32 v74, v74, v75
	v_add_u32_e32 v75, 19, v52
	v_cvt_f32_i32_e32 v75, v75
	v_mul_f32_e32 v74, v74, v53
	v_mul_f32_e32 v76, 0.15915494, v74
	v_floor_f32_e32 v76, v76
	v_fma_f32 v74, v74, 0.15915494, -v76
	v_mul_f32_e32 v76, 0xbed49a78, v75
	v_cmp_gt_f32_e32 vcc, s91, v76
	v_lshlrev_b32_e32 v48, 16, v44
	v_and_b32_e32 v49, 0xffff0000, v44
	v_cndmask_b32_e32 v76, 0, v206, vcc
	v_fmac_f32_e32 v76, 0xbed49a78, v75
	v_exp_f32_e32 v75, v76
	v_cndmask_b32_e32 v77, 0, v207, vcc
	v_lshlrev_b32_e32 v92, 16, v47
	v_and_b32_e32 v93, 0xffff0000, v47
	v_ldexp_f32 v75, v75, v77
	v_add_u32_e32 v77, 20, v52
	v_cvt_f32_i32_e32 v77, v77
	v_mul_f32_e32 v75, v75, v53
	v_mul_f32_e32 v78, 0.15915494, v75
	v_floor_f32_e32 v78, v78
	v_fma_f32 v75, v75, 0.15915494, -v78
	v_mul_f32_e32 v78, 0xbed49a78, v77
	v_cmp_gt_f32_e32 vcc, s91, v78
	v_lshlrev_b32_e32 v44, 16, v43
	v_and_b32_e32 v45, 0xffff0000, v43
	v_cndmask_b32_e32 v78, 0, v206, vcc
	v_fmac_f32_e32 v78, 0xbed49a78, v77
	v_exp_f32_e32 v78, v78
	v_cndmask_b32_e32 v79, 0, v207, vcc
	v_lshlrev_b32_e32 v94, 16, v46
	v_and_b32_e32 v95, 0xffff0000, v46
	v_ldexp_f32 v78, v78, v79
	v_add_u32_e32 v79, 21, v52
	v_cvt_f32_i32_e32 v79, v79
	v_mul_f32_e32 v78, v78, v53
	v_mul_f32_e32 v80, 0.15915494, v78
	v_floor_f32_e32 v80, v80
	v_fma_f32 v78, v78, 0.15915494, -v80
	v_mul_f32_e32 v80, 0xbed49a78, v79
	v_cmp_gt_f32_e32 vcc, s91, v80
	v_lshlrev_b32_e32 v46, 16, v42
	v_and_b32_e32 v47, 0xffff0000, v42
	v_cndmask_b32_e32 v80, 0, v206, vcc
	v_fmac_f32_e32 v80, 0xbed49a78, v79
	v_exp_f32_e32 v79, v80
	v_cndmask_b32_e32 v81, 0, v207, vcc
	v_lshlrev_b32_e32 v96, 16, v41
	v_and_b32_e32 v97, 0xffff0000, v41
	v_ldexp_f32 v79, v79, v81
	v_add_u32_e32 v81, 22, v52
	v_cvt_f32_i32_e32 v81, v81
	v_mul_f32_e32 v79, v79, v53
	v_mul_f32_e32 v82, 0.15915494, v79
	v_floor_f32_e32 v82, v82
	v_lshlrev_b32_e32 v42, 16, v37
	v_and_b32_e32 v43, 0xffff0000, v37
	v_lshlrev_b32_e32 v40, 16, v36
	v_and_b32_e32 v41, 0xffff0000, v36
	v_pk_mul_f32 v[36:37], v[126:127], v[126:127]
	v_add_f32_e32 v34, v135, v34
	v_fma_f32 v79, v79, 0.15915494, -v82
	v_mul_f32_e32 v82, 0xbed49a78, v81
	v_add_f32_e32 v34, v36, v34
	v_cmp_gt_f32_e32 vcc, s91, v82
	v_pk_mul_f32 v[122:123], v[96:97], v[96:97]
	v_add_f32_e32 v34, v37, v34
	v_cndmask_b32_e32 v82, 0, v206, vcc
	v_add_f32_e32 v34, v122, v34
	v_fmac_f32_e32 v82, 0xbed49a78, v81
	v_pk_mul_f32 v[118:119], v[94:95], v[94:95]
	v_add_f32_e32 v34, v123, v34
	v_exp_f32_e32 v82, v82
	v_add_f32_e32 v34, v118, v34
	v_pk_mul_f32 v[114:115], v[92:93], v[92:93]
	v_add_f32_e32 v34, v119, v34
	v_add_f32_e32 v34, v114, v34
	v_cndmask_b32_e32 v83, 0, v207, vcc
	v_pk_mul_f32 v[110:111], v[90:91], v[90:91]
	v_add_f32_e32 v34, v115, v34
	v_ldexp_f32 v82, v82, v83
	v_add_u32_e32 v83, 23, v52
	v_add_f32_e32 v34, v110, v34
	v_cvt_f32_i32_e32 v83, v83
	v_pk_mul_f32 v[108:109], v[88:89], v[88:89]
	v_add_f32_e32 v34, v111, v34
	v_mul_f32_e32 v82, v82, v53
	v_add_f32_e32 v34, v108, v34
	v_mul_f32_e32 v84, 0.15915494, v82
	v_pk_mul_f32 v[140:141], v[38:39], v[38:39]
	v_add_f32_e32 v34, v109, v34
	v_floor_f32_e32 v84, v84
	v_add_f32_e32 v34, v140, v34
	v_fma_f32 v82, v82, 0.15915494, -v84
; #define MFMA32(a, b, c) __builtin_amdgcn_mfma_f32_32x32x16_bf16((a), (b), (c), 0, 0, 0)
; DI unsigned cvtpk(float lo, float hi) { f32x2_t v = {lo, hi}; bf16x2_t b = __builtin_convertvector(v, bf16x2_t); return __builtin_bit_cast(unsigned, b); }
; DI float bperm(float v, int x32) { return __builtin_bit_cast(float, __builtin_amdgcn_ds_bpermute(x32, __builtin_bit_cast(int, v))); }
; DI void rope_q(bf16x8 (&qf)[4], const float* gq, int pos, int hi, int x32) {
;     ...
;     for (int kk = 0; kk < 4; ++kk)
; #pragma unroll
;         for (int j = 0; j < 8; ++j) ss += v[kk][j] * v[kk][j];
;     ss += bperm(ss, x32);
;     const float rstd = rsqrtf(ss * (1.f / 64.f) + EPS);
; #pragma unroll
;     for (int kk = 0; kk < 4; ++kk) { const f32x4 g0 = *(const f32x4*)(gq + 16 * kk + 8 * hi), g1 = *(const f32x4*)(gq + 16 * kk + 8 * hi + 4);
; #pragma unroll
;         for (int j = 0; j < 4; ++j) { v[kk][j] = v[kk][j] * rstd * g0[j]; v[kk][4 + j] = v[kk][4 + j] * rstd * g1[j]; } }
; #pragma unroll
;     for (int kk = 0; kk < 2; ++kk)
; #pragma unroll
;         for (int j = 0; j < 8; ++j) {
;             const float invf = exp2f(-(float)(16 * kk + 8 * hi + j) * (13.287712379549449f / 32.f));
;             float r = (float)pos * invf * 0.15915494309189535f; r = r - floorf(r);
;             const float cs = __builtin_amdgcn_cosf(r), sn = __builtin_amdgcn_sinf(r);
;             const float x1 = v[kk][j], x2 = v[kk + 2][j];
;             v[kk][j] = x1 * cs - x2 * sn; v[kk + 2][j] = x2 * cs + x1 * sn; }
; #pragma unroll
;     for (int kk = 0; kk < 4; ++kk) { v4u w; w.x = cvtpk(v[kk][0], v[kk][1]); w.y = cvtpk(v[kk][2], v[kk][3]); w.z = cvtpk(v[kk][4], v[kk][5]); w.w = cvtpk(v[kk][6], v[kk][7]); qf[kk] = __builtin_bit_cast(bf16x8, w); }
; }
; DI unsigned moba_select(const bf16x8 (&qf)[4], const bf16* kmean, int b, int h, int own, int hi, int col, int x32) {
;     unsigned selmask = 0u;
;     const char* kmb = (const char*)(kmean + (size_t)((b * 16 + h) * 16) * 64);
;     const unsigned kmo = (unsigned)((col & 15) * 64 + 8 * hi) * 2u;
;     f32x16 g = zero16();
; #pragma unroll
;     for (int kk = 0; kk < 4; ++kk) { const bf16x8 kf = *(const bf16x8*)(kmb + kmo + 32 * kk); g = MFMA32(kf, qf[kk], g); }
	v_mul_f32_e32 v84, 0xbed49a78, v83
	v_pk_mul_f32 v[136:137], v[132:133], v[132:133]
	v_add_f32_e32 v34, v141, v34
	v_cmp_gt_f32_e32 vcc, s91, v84
	v_add_f32_e32 v34, v136, v34
	v_pk_mul_f32 v[128:129], v[40:41], v[40:41]
	v_cndmask_b32_e32 v84, 0, v206, vcc
	v_add_f32_e32 v34, v137, v34
	v_fmac_f32_e32 v84, 0xbed49a78, v83
	v_add_f32_e32 v34, v128, v34
	v_exp_f32_e32 v83, v84
	v_pk_mul_f32 v[124:125], v[42:43], v[42:43]
	v_add_f32_e32 v34, v129, v34
	v_add_f32_e32 v34, v124, v34
	v_pk_mul_f32 v[120:121], v[46:47], v[46:47]
	v_add_f32_e32 v34, v125, v34
	v_cndmask_b32_e32 v85, 0, v207, vcc
	v_add_f32_e32 v34, v120, v34
	v_ldexp_f32 v83, v83, v85
	v_add_f32_e32 v85, v121, v34
	v_lshlrev_b32_e32 v34, 7, v104
	v_and_b32_e32 v34, 0x780, v34
	v_lshl_add_u32 v118, v105, 4, v34
	global_load_dwordx4 v[34:37], v118, s[4:5]
	global_load_dwordx4 v[108:111], v118, s[4:5] offset:32
	v_pk_mul_f32 v[116:117], v[44:45], v[44:45]
	v_pk_mul_f32 v[112:113], v[48:49], v[48:49]
	v_add_f32_e32 v85, v116, v85
	v_add_f32_e32 v85, v117, v85
	v_add_f32_e32 v85, v112, v85
	v_add_f32_e32 v85, v113, v85
	global_load_dwordx4 v[112:115], v118, s[4:5] offset:64
	v_pk_mul_f32 v[102:103], v[86:87], v[86:87]
	global_load_dwordx4 v[116:119], v118, s[4:5] offset:96
	v_add_f32_e32 v85, v102, v85
	v_add_f32_e32 v85, v103, v85
	ds_bpermute_b32 v102, v106, v85
	v_mul_f32_e32 v53, v83, v53
	v_mul_f32_e32 v83, 0.15915494, v53
	v_floor_f32_e32 v83, v83
	v_fma_f32 v53, v53, 0.15915494, -v83
	s_waitcnt lgkmcnt(0)
	v_add_f32_e32 v85, v85, v102
	v_fmamk_f32 v85, v85, 0x3c800000, v204
	v_mul_f32_e32 v102, 0x4b800000, v85
	v_cmp_gt_f32_e32 vcc, s92, v85
	v_sin_f32_e32 v83, v53
	v_cos_f32_e32 v60, v58
	v_cndmask_b32_e32 v85, v85, v102, vcc
	v_rsq_f32_e32 v102, v85
	v_cos_f32_e32 v85, v53
	v_sin_f32_e32 v58, v58
	v_cos_f32_e32 v61, v59
	v_mul_f32_e32 v53, 0x45800000, v102
	v_cndmask_b32_e32 v102, v102, v53, vcc
	v_mul_f32_e32 v102, s93, v102
	v_pk_mul_f32 v[90:91], v[102:103], v[90:91] op_sel_hi:[0,1]
	v_pk_mul_f32 v[90:91], v[2:3], v[90:91]
	v_pk_mul_f32 v[2:3], v[102:103], v[92:93] op_sel_hi:[0,1]
	v_pk_mul_f32 v[92:93], v[12:13], v[2:3]
	v_pk_mul_f32 v[2:3], v[102:103], v[88:89] op_sel_hi:[0,1]
	v_pk_mul_f32 v[88:89], v[4:5], v[2:3]
	v_pk_mul_f32 v[2:3], v[102:103], v[38:39] op_sel_hi:[0,1]
	v_sin_f32_e32 v59, v59
	v_pk_mul_f32 v[2:3], v[14:15], v[2:3]
	v_pk_mul_f32 v[12:13], v[102:103], v[42:43] op_sel_hi:[0,1]
	v_pk_mul_f32 v[14:15], v[102:103], v[48:49] op_sel_hi:[0,1]
	v_cos_f32_e32 v64, v62
	v_sin_f32_e32 v62, v62
	v_cos_f32_e32 v65, v63
	v_sin_f32_e32 v63, v63
	v_pk_mul_f32 v[120:121], v[102:103], v[138:139] op_sel_hi:[0,1]
	v_pk_mul_f32 v[4:5], v[102:103], v[40:41] op_sel_hi:[0,1]
	v_pk_mul_f32 v[8:9], v[8:9], v[12:13]
	v_pk_mul_f32 v[12:13], v[102:103], v[46:47] op_sel_hi:[0,1]
	v_pk_mul_f32 v[18:19], v[18:19], v[14:15]
	v_pk_mul_f32 v[14:15], v[102:103], v[44:45] op_sel_hi:[0,1]
	v_cos_f32_e32 v68, v66
	v_sin_f32_e32 v66, v66
	v_cos_f32_e32 v69, v67
	v_sin_f32_e32 v67, v67
	v_pk_mul_f32 v[30:31], v[30:31], v[120:121]
	v_pk_mul_f32 v[120:121], v[102:103], v[126:127] op_sel_hi:[0,1]
	v_pk_mul_f32 v[4:5], v[6:7], v[4:5]
	v_pk_mul_f32 v[6:7], v[102:103], v[132:133] op_sel_hi:[0,1]
	v_pk_mul_f32 v[12:13], v[22:23], v[12:13]
	v_pk_mul_f32 v[22:23], v[24:25], v[14:15]
	v_pk_mul_f32 v[14:15], v[102:103], v[86:87] op_sel_hi:[0,1]
	v_cos_f32_e32 v72, v70
	v_sin_f32_e32 v70, v70
	v_cos_f32_e32 v73, v71
	v_sin_f32_e32 v71, v71
	v_pk_mul_f32 v[26:27], v[26:27], v[120:121]
	v_pk_mul_f32 v[120:121], v[102:103], v[130:131] op_sel_hi:[0,1]
	v_pk_mul_f32 v[6:7], v[16:17], v[6:7]
	v_pk_mul_f32 v[20:21], v[20:21], v[14:15]
	v_pk_mul_f32 v[14:15], v[54:55], v[2:3]
	v_pk_mul_f32 v[2:3], v[56:57], v[2:3]
	v_pk_mul_f32 v[32:33], v[32:33], v[120:121]
	v_pk_fma_f32 v[24:25], v[54:55], v[30:31], v[2:3]
	v_pk_mul_f32 v[2:3], v[58:59], v[6:7]
	v_pk_mul_f32 v[6:7], v[60:61], v[6:7]
	v_cos_f32_e32 v76, v74
	v_sin_f32_e32 v74, v74
	v_cos_f32_e32 v77, v75
	v_sin_f32_e32 v75, v75
	v_pk_mul_f32 v[96:97], v[102:103], v[96:97] op_sel_hi:[0,1]
	v_pk_fma_f32 v[14:15], v[56:57], v[30:31], v[14:15] neg_lo:[0,0,1] neg_hi:[0,0,1]
	v_pk_fma_f32 v[30:31], v[58:59], v[32:33], v[6:7]
	v_pk_mul_f32 v[6:7], v[62:63], v[4:5]
	v_pk_mul_f32 v[4:5], v[64:65], v[4:5]
	v_pk_mul_f32 v[28:29], v[28:29], v[96:97]
	v_pk_mul_f32 v[94:95], v[102:103], v[94:95] op_sel_hi:[0,1]
	v_pk_fma_f32 v[6:7], v[64:65], v[26:27], v[6:7] neg_lo:[0,0,1] neg_hi:[0,0,1]
	v_pk_fma_f32 v[26:27], v[62:63], v[26:27], v[4:5]
	v_pk_mul_f32 v[4:5], v[66:67], v[8:9]
	v_pk_mul_f32 v[8:9], v[68:69], v[8:9]
	v_pk_mul_f32 v[10:11], v[10:11], v[94:95]
	v_pk_fma_f32 v[4:5], v[68:69], v[28:29], v[4:5] neg_lo:[0,0,1] neg_hi:[0,0,1]
	v_pk_fma_f32 v[28:29], v[66:67], v[28:29], v[8:9]
	v_pk_mul_f32 v[8:9], v[70:71], v[12:13]
	v_pk_fma_f32 v[2:3], v[60:61], v[32:33], v[2:3] neg_lo:[0,0,1] neg_hi:[0,0,1]
	v_pk_fma_f32 v[32:33], v[72:73], v[10:11], v[8:9] neg_lo:[0,0,1] neg_hi:[0,0,1]
	v_pk_mul_f32 v[8:9], v[72:73], v[12:13]
	v_cvt_pk_bf16_f32 v66, v14, v15
	v_pk_fma_f32 v[38:39], v[70:71], v[10:11], v[8:9]
	v_pk_mul_f32 v[8:9], v[74:75], v[22:23]
	v_cvt_pk_bf16_f32 v67, v2, v3
	v_cvt_pk_bf16_f32 v68, v6, v7
	v_cvt_pk_bf16_f32 v69, v4, v5
	v_pk_fma_f32 v[40:41], v[76:77], v[92:93], v[8:9] neg_lo:[0,0,1] neg_hi:[0,0,1]
	v_cos_f32_e32 v80, v78
	s_waitcnt vmcnt(3)
; #define MFMA32(a, b, c) __builtin_amdgcn_mfma_f32_32x32x16_bf16((a), (b), (c), 0, 0, 0)
; DI float bperm(float v, int x32) { return __builtin_bit_cast(float, __builtin_amdgcn_ds_bpermute(x32, __builtin_bit_cast(int, v))); }
; DI int bperm_i(int v, int x32) { return __builtin_amdgcn_ds_bpermute(x32, v); }
; DI unsigned moba_select(const bf16x8 (&qf)[4], const bf16* kmean, int b, int h, int own, int hi, int col, int x32) {
;     ...
;     for (int kk = 0; kk < 4; ++kk) { const bf16x8 kf = *(const bf16x8*)(kmb + kmo + 32 * kk); g = MFMA32(kf, qf[kk], g); }
;     float val[8];
;     const int own4 = own - 4 * hi;
; #pragma unroll
;     for (int i = 0; i < 8; ++i) val[i] = ((i & 3) + 8 * (i >> 2) < own4) ? g[i] : -INFINITY;
;     float lv[3]; int ln[3];
; #pragma unroll
;     for (int r = 0; r < 3; ++r) { float best = -INFINITY; int bi = 8;
; #pragma unroll
;         for (int i = 0; i < 8; ++i) if (val[i] > best) { best = val[i]; bi = i; }
; #pragma unroll
;         for (int i = 0; i < 8; ++i) if (bi == i) val[i] = -INFINITY;
;         lv[r] = best; ln[r] = (bi < 8) ? ((bi & 3) + 8 * (bi >> 2) + 4 * hi) : 99; }
;     float cv[6]; int cn[6];
; #pragma unroll
;     for (int r = 0; r < 3; ++r) { const float pv = bperm(lv[r], x32); const int pn = bperm_i(ln[r], x32);
;         cv[r] = hi ? pv : lv[r]; cn[r] = hi ? pn : ln[r]; cv[3 + r] = hi ? lv[r] : pv; cn[3 + r] = hi ? ln[r] : pn; }
	v_mfma_f32_32x32x16_bf16 v[2:17], v[34:37], v[66:69], 0
	v_sin_f32_e32 v78, v78
	v_cos_f32_e32 v81, v79
	v_sin_f32_e32 v79, v79
	v_cos_f32_e32 v84, v82
	v_sin_f32_e32 v82, v82
	v_cvt_pk_bf16_f32 v70, v32, v33
	v_pk_mul_f32 v[42:43], v[78:79], v[18:19]
	v_cvt_pk_bf16_f32 v71, v40, v41
	v_pk_mul_f32 v[36:37], v[82:83], v[20:21]
	v_pk_fma_f32 v[34:35], v[80:81], v[90:91], v[42:43] neg_lo:[0,0,1] neg_hi:[0,0,1]
	v_pk_fma_f32 v[36:37], v[84:85], v[88:89], v[36:37] neg_lo:[0,0,1] neg_hi:[0,0,1]
	v_cvt_pk_bf16_f32 v72, v34, v35
	v_cvt_pk_bf16_f32 v73, v36, v37
	v_pk_mul_f32 v[22:23], v[76:77], v[22:23]
	v_cvt_pk_bf16_f32 v76, v26, v27
	s_waitcnt vmcnt(2)
	v_mfma_f32_32x32x16_bf16 v[2:17], v[108:111], v[70:73], v[2:17]
	v_fma_f32 v22, v74, v92, v22
	v_fma_f32 v23, v75, v93, v23
	v_cvt_pk_bf16_f32 v74, v24, v25
	v_cvt_pk_bf16_f32 v75, v30, v31
	v_cvt_pk_bf16_f32 v77, v28, v29
	v_pk_mul_f32 v[18:19], v[80:81], v[18:19]
	v_pk_mul_f32 v[20:21], v[84:85], v[20:21]
	v_pk_fma_f32 v[18:19], v[78:79], v[90:91], v[18:19]
	s_waitcnt vmcnt(1)
	v_mfma_f32_32x32x16_bf16 v[2:17], v[112:115], v[74:77], v[2:17]
	v_fma_f32 v20, v82, v88, v20
	v_fma_f32 v21, v83, v89, v21
	v_cvt_pk_bf16_f32 v78, v38, v39
	v_cvt_pk_bf16_f32 v79, v22, v23
	v_cvt_pk_bf16_f32 v80, v18, v19
	v_cvt_pk_bf16_f32 v81, v20, v21
	v_lshlrev_b32_e32 v102, 2, v105
	s_waitcnt vmcnt(0)
	v_mfma_f32_32x32x16_bf16 v[2:17], v[116:119], v[78:81], v[2:17]
	s_nop 11
	v_sub_u32_e32 v10, s95, v102
	v_cmp_lt_i32_e32 vcc, 0, v10
	s_nop 1
	v_cndmask_b32_e32 v2, v208, v2, vcc
	v_cmp_lt_i32_e32 vcc, 1, v10
	s_nop 1
	v_cndmask_b32_e32 v3, v208, v3, vcc
	v_cmp_lt_i32_e32 vcc, 2, v10
	s_nop 1
	v_cndmask_b32_e32 v4, v208, v4, vcc
	v_cmp_lt_i32_e32 vcc, 3, v10
	s_nop 1
	v_cndmask_b32_e32 v5, v208, v5, vcc
	v_cmp_lt_i32_e32 vcc, 8, v10
	s_nop 1
	v_cndmask_b32_e32 v6, v208, v6, vcc
	v_cmp_lt_i32_e32 vcc, 9, v10
	s_nop 1
	v_cndmask_b32_e32 v7, v208, v7, vcc
	v_cmp_lt_i32_e32 vcc, 10, v10
	s_nop 1
	v_cndmask_b32_e32 v8, v208, v8, vcc
	v_cmp_lt_i32_e32 vcc, 11, v10
	s_nop 1
	v_cndmask_b32_e32 v9, v208, v9, vcc
	v_cmp_lg_f32_e32 vcc, s56, v2
	s_nop 1
	v_cndmask_b32_e32 v10, v208, v2, vcc
	v_cndmask_b32_e64 v11, 8, 0, vcc
	v_cmp_gt_f32_e32 vcc, v3, v10
	s_nop 1
	v_cndmask_b32_e32 v10, v10, v3, vcc
	v_cndmask_b32_e64 v11, v11, 1, vcc
	v_cmp_gt_f32_e32 vcc, v4, v10
	s_nop 1
	v_cndmask_b32_e32 v10, v10, v4, vcc
	v_cndmask_b32_e64 v11, v11, 2, vcc
	v_cmp_gt_f32_e32 vcc, v5, v10
	s_nop 1
	v_cndmask_b32_e32 v10, v10, v5, vcc
	v_cndmask_b32_e64 v11, v11, 3, vcc
	v_cmp_gt_f32_e32 vcc, v6, v10
	s_nop 1
	v_cndmask_b32_e32 v10, v10, v6, vcc
	v_cndmask_b32_e64 v11, v11, 4, vcc
	v_cmp_gt_f32_e32 vcc, v7, v10
	s_nop 1
	v_cndmask_b32_e32 v10, v10, v7, vcc
	v_cndmask_b32_e64 v11, v11, 5, vcc
	v_cmp_gt_f32_e32 vcc, v8, v10
	s_nop 1
	v_cndmask_b32_e32 v10, v10, v8, vcc
	v_cndmask_b32_e64 v11, v11, 6, vcc
	v_cmp_ngt_f32_e64 s[4:5], v9, v10
	s_and_b64 vcc, vcc, s[4:5]
	v_cndmask_b32_e32 v8, v8, v208, vcc
	v_cndmask_b32_e64 v11, 7, v11, s[4:5]
	v_cmp_ne_u32_e64 s[6:7], 0, v11
	v_cndmask_b32_e64 v12, v208, v9, s[4:5]
	v_cndmask_b32_e64 v9, v9, v10, s[4:5]
	v_cndmask_b32_e64 v2, v208, v2, s[6:7]
	v_cmp_ne_u32_e64 s[6:7], 1, v11
	v_lshlrev_b32_e32 v10, 1, v11
	v_and_b32_e32 v10, 8, v10
	v_cndmask_b32_e64 v3, v208, v3, s[6:7]
	v_cmp_ne_u32_e64 s[6:7], 2, v11
	v_and_or_b32 v13, v11, 3, v102
	v_add_u32_e32 v10, v13, v10
	v_cndmask_b32_e64 v4, v208, v4, s[6:7]
	v_cmp_ne_u32_e64 s[6:7], 3, v11
	v_cmp_gt_u32_e32 vcc, 8, v11
	s_nop 0
	v_cndmask_b32_e64 v5, v208, v5, s[6:7]
	v_cmp_ne_u32_e64 s[6:7], 4, v11
	v_cndmask_b32_e32 v10, v209, v10, vcc
	v_cmp_lg_f32_e32 vcc, s56, v2
	v_cndmask_b32_e64 v6, v208, v6, s[6:7]
	v_cmp_ne_u32_e64 s[6:7], 5, v11
	v_cndmask_b32_e32 v11, v208, v2, vcc
	v_cndmask_b32_e64 v13, 8, 0, vcc
	v_cmp_gt_f32_e32 vcc, v3, v11
	v_cndmask_b32_e64 v7, v208, v7, s[6:7]
	s_nop 0
	v_cndmask_b32_e32 v11, v11, v3, vcc
	v_cndmask_b32_e64 v13, v13, 1, vcc
	v_cmp_gt_f32_e32 vcc, v4, v11
	s_nop 1
	v_cndmask_b32_e32 v11, v11, v4, vcc
	v_cndmask_b32_e64 v13, v13, 2, vcc
	v_cmp_gt_f32_e32 vcc, v5, v11
	s_nop 1
	v_cndmask_b32_e32 v11, v11, v5, vcc
	v_cndmask_b32_e64 v13, v13, 3, vcc
	v_cmp_gt_f32_e32 vcc, v6, v11
	s_nop 1
	v_cndmask_b32_e32 v11, v11, v6, vcc
	v_cndmask_b32_e64 v13, v13, 4, vcc
	v_cmp_gt_f32_e32 vcc, v7, v11
	s_nop 1
	v_cndmask_b32_e32 v11, v11, v7, vcc
	v_cndmask_b32_e64 v13, v13, 5, vcc
	v_cmp_gt_f32_e32 vcc, v8, v11
	s_nop 1
	v_cndmask_b32_e32 v11, v11, v8, vcc
	v_cndmask_b32_e64 v13, v13, 6, vcc
	v_cmp_ngt_f32_e64 s[4:5], v12, v11
	s_and_b64 vcc, vcc, s[4:5]
	v_cndmask_b32_e32 v8, v8, v208, vcc
	v_cndmask_b32_e64 v13, 7, v13, s[4:5]
	v_cmp_ne_u32_e64 s[6:7], 0, v13
	v_cndmask_b32_e64 v14, v208, v12, s[4:5]
	v_cndmask_b32_e64 v11, v12, v11, s[4:5]
	v_lshlrev_b32_e32 v12, 1, v13
	v_cndmask_b32_e64 v2, v208, v2, s[6:7]
	v_cmp_ne_u32_e64 s[6:7], 1, v13
	v_and_b32_e32 v12, 8, v12
	v_and_or_b32 v15, v13, 3, v102
	v_cndmask_b32_e64 v3, v208, v3, s[6:7]
	v_cmp_ne_u32_e64 s[6:7], 2, v13
	v_add_u32_e32 v12, v15, v12
	v_cmp_gt_u32_e32 vcc, 8, v13
	v_cndmask_b32_e64 v4, v208, v4, s[6:7]
	v_cmp_ne_u32_e64 s[6:7], 3, v13
	v_cndmask_b32_e32 v12, v209, v12, vcc
	v_cmp_lg_f32_e32 vcc, s56, v2
	v_cndmask_b32_e64 v5, v208, v5, s[6:7]
	v_cmp_ne_u32_e64 s[6:7], 4, v13
	v_cndmask_b32_e32 v2, v208, v2, vcc
	s_nop 0
	v_cndmask_b32_e64 v6, v208, v6, s[6:7]
	v_cmp_ne_u32_e64 s[6:7], 5, v13
	v_cndmask_b32_e64 v13, 8, 0, vcc
	v_cmp_gt_f32_e32 vcc, v3, v2
	v_cndmask_b32_e64 v7, v208, v7, s[6:7]
	s_nop 0
	v_cndmask_b32_e32 v2, v2, v3, vcc
	v_cndmask_b32_e64 v3, v13, 1, vcc
	v_cmp_gt_f32_e32 vcc, v4, v2
	s_nop 1
	v_cndmask_b32_e32 v2, v2, v4, vcc
	v_cndmask_b32_e64 v3, v3, 2, vcc
	v_cmp_gt_f32_e32 vcc, v5, v2
	s_nop 1
	v_cndmask_b32_e32 v2, v2, v5, vcc
	v_cndmask_b32_e64 v3, v3, 3, vcc
	v_cmp_gt_f32_e32 vcc, v6, v2
	s_nop 1
	v_cndmask_b32_e32 v2, v2, v6, vcc
	v_cndmask_b32_e64 v3, v3, 4, vcc
	v_cmp_gt_f32_e32 vcc, v7, v2
	ds_bpermute_b32 v6, v106, v10
	s_nop 0
	v_cndmask_b32_e32 v2, v2, v7, vcc
	v_cndmask_b32_e64 v3, v3, 5, vcc
	v_cmp_gt_f32_e32 vcc, v8, v2
	ds_bpermute_b32 v7, v106, v11
	s_nop 0
	v_cndmask_b32_e32 v2, v2, v8, vcc
	v_cndmask_b32_e64 v3, v3, 6, vcc
	v_cmp_gt_f32_e32 vcc, v14, v2
	s_nop 1
	v_cndmask_b32_e64 v3, v3, 7, vcc
	v_lshlrev_b32_e32 v4, 1, v3
	v_and_b32_e32 v4, 8, v4
	v_and_or_b32 v5, v3, 3, v102
	v_add_u32_e32 v4, v5, v4
	ds_bpermute_b32 v5, v106, v9
	v_cndmask_b32_e32 v2, v2, v14, vcc
	v_cmp_gt_u32_e32 vcc, 8, v3
	ds_bpermute_b32 v13, v106, v2
	s_nop 0
	v_cndmask_b32_e32 v3, v209, v4, vcc
	v_cmp_gt_u32_e32 vcc, 32, v104
	ds_bpermute_b32 v14, v106, v3
	s_waitcnt lgkmcnt(2)
; DI float bperm(float v, int x32) { return __builtin_bit_cast(float, __builtin_amdgcn_ds_bpermute(x32, __builtin_bit_cast(int, v))); }
; DI int bperm_i(int v, int x32) { return __builtin_amdgcn_ds_bpermute(x32, v); }
; DI unsigned moba_select(const bf16x8 (&qf)[4], const bf16* kmean, int b, int h, int own, int hi, int col, int x32) {
;     ...
;     for (int r = 0; r < 3; ++r) { const float pv = bperm(lv[r], x32); const int pn = bperm_i(ln[r], x32);
;         cv[r] = hi ? pv : lv[r]; cn[r] = hi ? pn : ln[r]; cv[3 + r] = hi ? lv[r] : pv; cn[3 + r] = hi ? ln[r] : pn; }
; #pragma unroll
;     for (int r = 0; r < 3; ++r) { float best = -INFINITY; int bi = 6;
; #pragma unroll
;         for (int i = 0; i < 6; ++i) if (cv[i] > best) { best = cv[i]; bi = i; }
;         int bn = 99;
; #pragma unroll
;         for (int i = 0; i < 6; ++i) if (bi == i) { cv[i] = -INFINITY; bn = cn[i]; }
;         if (bn < 16) selmask |= 1u << bn; }
;     return selmask;
	v_cndmask_b32_e32 v4, v5, v9, vcc
	v_cndmask_b32_e32 v5, v9, v5, vcc
	ds_bpermute_b32 v9, v106, v12
	v_cndmask_b32_e32 v8, v6, v10, vcc
	v_cndmask_b32_e32 v6, v10, v6, vcc
	v_cndmask_b32_e32 v10, v7, v11, vcc
	v_cndmask_b32_e32 v7, v11, v7, vcc
	s_waitcnt lgkmcnt(0)
	v_cndmask_b32_e32 v15, v9, v12, vcc
	v_cndmask_b32_e32 v9, v12, v9, vcc
	v_cndmask_b32_e32 v11, v13, v2, vcc
	v_cndmask_b32_e32 v12, v14, v3, vcc
	v_cndmask_b32_e32 v2, v2, v13, vcc
	v_cndmask_b32_e32 v3, v3, v14, vcc
	v_cmp_lg_f32_e32 vcc, s56, v4
	s_nop 1
	v_cndmask_b32_e32 v13, v208, v4, vcc
	v_cndmask_b32_e64 v14, 6, 0, vcc
	v_cmp_gt_f32_e32 vcc, v10, v13
	s_nop 1
	v_cndmask_b32_e32 v13, v13, v10, vcc
	v_cndmask_b32_e64 v14, v14, 1, vcc
	v_cmp_gt_f32_e32 vcc, v11, v13
	s_nop 1
	v_cndmask_b32_e32 v13, v13, v11, vcc
	v_cndmask_b32_e64 v14, v14, 2, vcc
	v_cmp_gt_f32_e32 vcc, v5, v13
	s_nop 1
	v_cndmask_b32_e32 v13, v13, v5, vcc
	v_cndmask_b32_e64 v14, v14, 3, vcc
	v_cmp_gt_f32_e32 vcc, v7, v13
	s_nop 1
	v_cndmask_b32_e32 v13, v13, v7, vcc
	v_cndmask_b32_e64 v14, v14, 4, vcc
	v_cmp_ngt_f32_e64 s[4:5], v2, v13
	s_and_b64 vcc, vcc, s[4:5]
	v_cndmask_b32_e32 v7, v7, v208, vcc
	v_cndmask_b32_e64 v13, 5, v14, s[4:5]
	v_cmp_eq_u32_e64 s[6:7], 0, v13
	v_cndmask_b32_e64 v2, v208, v2, s[4:5]
	s_nop 0
	v_cndmask_b32_e64 v4, v4, v208, s[6:7]
	v_cndmask_b32_e64 v14, v209, v8, s[6:7]
	v_cmp_eq_u32_e64 s[6:7], 1, v13
	s_nop 1
	v_cndmask_b32_e64 v10, v10, v208, s[6:7]
	v_cndmask_b32_e64 v14, v14, v15, s[6:7]
	v_cmp_eq_u32_e64 s[6:7], 2, v13
	s_nop 1
	v_cndmask_b32_e64 v11, v11, v208, s[6:7]
	v_cndmask_b32_e64 v14, v14, v12, s[6:7]
	v_cmp_eq_u32_e64 s[6:7], 3, v13
	s_nop 1
	v_cndmask_b32_e64 v13, v14, v6, s[6:7]
	v_cndmask_b32_e32 v13, v13, v9, vcc
	v_cndmask_b32_e64 v13, v3, v13, s[4:5]
	v_lshlrev_b32_e64 v14, v13, 1
	v_cmp_gt_i32_e32 vcc, 16, v13
	v_cndmask_b32_e64 v5, v5, v208, s[6:7]
	s_nop 0
	v_cndmask_b32_e32 v13, 0, v14, vcc
	v_cmp_lg_f32_e32 vcc, s56, v4
	s_nop 1
	v_cndmask_b32_e32 v14, v208, v4, vcc
	v_cndmask_b32_e64 v16, 6, 0, vcc
	v_cmp_gt_f32_e32 vcc, v10, v14
	s_nop 1
	v_cndmask_b32_e32 v14, v14, v10, vcc
	v_cndmask_b32_e64 v16, v16, 1, vcc
	v_cmp_gt_f32_e32 vcc, v11, v14
	s_nop 1
	v_cndmask_b32_e32 v14, v14, v11, vcc
	v_cndmask_b32_e64 v16, v16, 2, vcc
	v_cmp_gt_f32_e32 vcc, v5, v14
	s_nop 1
	v_cndmask_b32_e32 v14, v14, v5, vcc
	v_cndmask_b32_e64 v16, v16, 3, vcc
	v_cmp_gt_f32_e32 vcc, v7, v14
	s_nop 1
	v_cndmask_b32_e32 v14, v14, v7, vcc
	v_cndmask_b32_e64 v16, v16, 4, vcc
	v_cmp_ngt_f32_e64 s[4:5], v2, v14
	s_and_b64 vcc, vcc, s[4:5]
	v_cndmask_b32_e32 v7, v7, v208, vcc
	v_cndmask_b32_e64 v14, 5, v16, s[4:5]
	v_cmp_eq_u32_e64 s[6:7], 0, v14
	v_cndmask_b32_e64 v2, v208, v2, s[4:5]
	s_cmp_lg_u32 s95, 0
	v_cndmask_b32_e64 v4, v4, v208, s[6:7]
	v_cndmask_b32_e64 v16, v209, v8, s[6:7]
	v_cmp_eq_u32_e64 s[6:7], 1, v14
	s_nop 1
	v_cndmask_b32_e64 v10, v10, v208, s[6:7]
	v_cndmask_b32_e64 v16, v16, v15, s[6:7]
	v_cmp_eq_u32_e64 s[6:7], 2, v14
	s_nop 1
	v_cndmask_b32_e64 v11, v11, v208, s[6:7]
	v_cndmask_b32_e64 v16, v16, v12, s[6:7]
	v_cmp_eq_u32_e64 s[6:7], 3, v14
	s_nop 1
	v_cndmask_b32_e64 v14, v16, v6, s[6:7]
	v_cndmask_b32_e32 v14, v14, v9, vcc
	v_cndmask_b32_e64 v14, v3, v14, s[4:5]
	v_lshlrev_b32_e64 v16, v14, 1
	v_cmp_gt_i32_e32 vcc, 16, v14
	v_cndmask_b32_e64 v5, v5, v208, s[6:7]
	s_nop 0
	v_cndmask_b32_e32 v14, 0, v16, vcc
	v_cmp_lg_f32_e32 vcc, s56, v4
	s_nop 1
	v_cndmask_b32_e32 v4, v208, v4, vcc
	v_cndmask_b32_e64 v16, 6, 0, vcc
	v_cmp_gt_f32_e32 vcc, v10, v4
	s_nop 1
	v_cndmask_b32_e32 v4, v4, v10, vcc
	v_cndmask_b32_e64 v10, v16, 1, vcc
	v_cmp_gt_f32_e32 vcc, v11, v4
	s_nop 1
	v_cndmask_b32_e32 v4, v4, v11, vcc
	v_cndmask_b32_e64 v10, v10, 2, vcc
	v_cmp_gt_f32_e32 vcc, v5, v4
	s_nop 1
	v_cndmask_b32_e32 v4, v4, v5, vcc
	v_cndmask_b32_e64 v5, v10, 3, vcc
	v_cmp_gt_f32_e32 vcc, v7, v4
	s_nop 1
	v_cndmask_b32_e32 v4, v4, v7, vcc
	v_cndmask_b32_e64 v5, v5, 4, vcc
	v_cmp_ngt_f32_e64 s[4:5], v2, v4
	s_nop 1
	v_cndmask_b32_e64 v2, 5, v5, s[4:5]
	v_cmp_eq_u32_e64 s[6:7], 0, v2
	s_nop 1
	v_cndmask_b32_e64 v4, v209, v8, s[6:7]
	v_cmp_eq_u32_e64 s[6:7], 1, v2
	s_nop 1
	v_cndmask_b32_e64 v4, v4, v15, s[6:7]
	v_cmp_eq_u32_e64 s[6:7], 2, v2
	s_nop 1
	v_cndmask_b32_e64 v4, v4, v12, s[6:7]
	v_cmp_eq_u32_e64 s[6:7], 3, v2
	s_nop 1
	v_cndmask_b32_e64 v2, v4, v6, s[6:7]
	v_cndmask_b32_e32 v2, v2, v9, vcc
	v_cndmask_b32_e64 v2, v3, v2, s[4:5]
	v_lshlrev_b32_e64 v3, v2, 1
	v_cmp_gt_i32_e32 vcc, 16, v2
	s_nop 1
	v_cndmask_b32_e32 v2, 0, v3, vcc
	v_or3_b32 v103, v14, v13, v2
	s_cbranch_scc0 .LBB0_518
	s_and_b32 s45, s95, 15
	s_mov_b32 s55, 0
	s_mov_b32 s4, 0

; #define LAS __attribute__((address_space(3)))
; template <int MODE>
; DI bool attn_tile(const bf16x8 (&kf)[4], const bf16x8 (&vf)[4], const bf16x8 (&qf)[4], int key0, int q0, int tq, int hi, int x32, int own, unsigned selmask,
;                   float& m_run, float& l_run, f32x16& O0, f32x16& O1) {
;     ...
;         const int blk = key0 >> 8; const float B2 = m_run;
;         if (key0 == q0) {
; #pragma unroll
;             for (int i = 0; i < 16; ++i) { const int key = key0 + 16 * (i >> 3) + 8 * hi + (i & 7); const float p = __builtin_amdgcn_exp2f((key <= tq) ? s[i] * SC2 - B2 : -INFINITY); s[i] = p; l_run += p; }
;         } else {
;             const float bsh = (blk == own || ((selmask >> blk) & 1u)) ? B2 : INFINITY;
; #pragma unroll
;             for (int i = 0; i < 16; ++i) { const float p = __builtin_amdgcn_exp2f(s[i] * SC2 - bsh); s[i] = p; l_run += p; }
; DI void moba_wg_phase(const bf16* qb, const unsigned char* kfb, const unsigned char* vfb, bf16* ob, const bf16* kmean, const float* gains, int G, LAS unsigned char* lds, const int wave_s) {
;     ...
;             const bool need = (n < own) ? (((anym >> n) & 1u) != 0u) : true;
;             if (need) { const int ntile = (n < own) ? 8 : (wave + 1);
;                 for (int t = 0; t < ntile; ++t) {
;                     const LAS unsigned char* sl = lds + (unsigned)(n & 1) * 65536u + (unsigned)t * 8192u + lofs; bf16x8 kf[4], vf[4];
;                     kf[0] = *(const LAS bf16x8*)(sl); kf[1] = *(const LAS bf16x8*)(sl + 1024); kf[2] = *(const LAS bf16x8*)(sl + 2048); kf[3] = *(const LAS bf16x8*)(sl + 3072);
;                     vf[0] = *(const LAS bf16x8*)(sl + 4096); vf[1] = *(const LAS bf16x8*)(sl + 5120); vf[2] = *(const LAS bf16x8*)(sl + 6144); vf[3] = *(const LAS bf16x8*)(sl + 7168);
;                     (void)attn_tile<1>(kf, vf, qf, n * 256 + 32 * t, q0, tq, hi, xq, own, selmask, m_run, l_run, O0, O1); } }
.LBB0_505:
	v_cndmask_b32_e64 v0, 0, 1, s[50:51]
	v_lshl_add_u32 v0, v0, 16, v107
	s_mov_b32 s97, s80
	v_lshrrev_b32_e32 v178, s45, v103
	v_and_b32_e32 v178, 1, v178
	v_cmp_eq_u32_e32 vcc, 1, v178
	s_cmp_eq_u32 s45, s95
	s_cselect_b64 s[58:59], -1, 0
	s_or_b64 vcc, vcc, s[58:59]
	v_xor_b32_e32 v179, 0x80000000, v99
	v_mov_b32_e32 v178, 0xff800000
	s_nop 1
	v_cndmask_b32_e32 v162, v178, v179, vcc
	v_mov_b32_e32 v163, v162
	v_mov_b32_e32 v164, v162
	v_mov_b32_e32 v165, v162
	v_mov_b32_e32 v166, v162
	v_mov_b32_e32 v167, v162
	v_mov_b32_e32 v168, v162
	v_mov_b32_e32 v169, v162
	v_mov_b32_e32 v170, v162
	v_mov_b32_e32 v171, v162
	v_mov_b32_e32 v172, v162
	v_mov_b32_e32 v173, v162
	v_mov_b32_e32 v174, v162
	v_mov_b32_e32 v175, v162
	v_mov_b32_e32 v176, v162
	v_mov_b32_e32 v177, v162
	s_waitcnt lgkmcnt(0)
	ds_read_b128 v[214:217], v0
	ds_read_b128 v[218:221], v0 offset:1024
	ds_read_b128 v[222:225], v0 offset:2048
	ds_read_b128 v[226:229], v0 offset:3072
	ds_read_b128 v[90:93], v0 offset:4096
	ds_read_b128 v[86:89], v0 offset:5120
	ds_read_b128 v[94:97], v0 offset:6144
	ds_read_b128 v[82:85], v0 offset:7168
	s_branch .LBB0_507

; template <int MODE>
; DI bool attn_tile(const bf16x8 (&kf)[4], const bf16x8 (&vf)[4], const bf16x8 (&qf)[4], int key0, int q0, int tq, int hi, int x32, int own, unsigned selmask,
;                   float& m_run, float& l_run, f32x16& O0, f32x16& O1) {
;     ...
;         const int blk = key0 >> 8; const float B2 = m_run;
;         if (key0 == q0) {
; #pragma unroll
;             for (int i = 0; i < 16; ++i) { const int key = key0 + 16 * (i >> 3) + 8 * hi + (i & 7); const float p = __builtin_amdgcn_exp2f((key <= tq) ? s[i] * SC2 - B2 : -INFINITY); s[i] = p; l_run += p; }
;         } else {
;             const float bsh = (blk == own || ((selmask >> blk) & 1u)) ? B2 : INFINITY;
; #pragma unroll
;             for (int i = 0; i < 16; ++i) { const float p = __builtin_amdgcn_exp2f(s[i] * SC2 - bsh); s[i] = p; l_run += p; }
;         }
;         pv_regs(vf, s, O0, O1);
.LBB0_507:
	s_cmp_lg_u32 s96, s97
	s_mov_b64 s[46:47], -1
	s_waitcnt lgkmcnt(4)
	v_mfma_f32_32x32x16_bf16 v[34:49], v[214:217], v[66:69], v[162:177]
	v_mfma_f32_32x32x16_bf16 v[34:49], v[218:221], v[70:73], v[34:49]
	v_mfma_f32_32x32x16_bf16 v[34:49], v[222:225], v[74:77], v[34:49]
	v_mfma_f32_32x32x16_bf16 v[34:49], v[226:229], v[78:81], v[34:49]
	ds_read_b128 v[214:217], v0 offset:8192
	ds_read_b128 v[218:221], v0 offset:9216
	ds_read_b128 v[222:225], v0 offset:10240
	ds_read_b128 v[226:229], v0 offset:11264
	s_cbranch_scc0 .LBB0_513
	s_nop 6
	v_exp_f32_e32 v50, v34
	v_exp_f32_e32 v51, v35
	v_exp_f32_e32 v52, v36
	v_add_f32_e32 v53, v108, v50
	v_add_f32_e32 v53, v51, v53
	v_add_f32_e32 v57, v52, v53
	v_exp_f32_e32 v53, v37
	v_exp_f32_e32 v54, v38
	v_exp_f32_e32 v55, v39
	v_exp_f32_e32 v56, v40
	v_add_f32_e32 v57, v53, v57
	v_add_f32_e32 v57, v54, v57
	v_add_f32_e32 v57, v55, v57
	v_add_f32_e32 v61, v56, v57
	v_exp_f32_e32 v57, v41
	v_exp_f32_e32 v58, v42
	v_exp_f32_e32 v59, v43
	v_exp_f32_e32 v60, v44
	v_add_f32_e32 v61, v57, v61
	v_add_f32_e32 v61, v58, v61
	v_add_f32_e32 v61, v59, v61
	v_add_f32_e32 v109, v60, v61
	v_exp_f32_e32 v61, v45
	v_exp_f32_e32 v62, v46
	v_exp_f32_e32 v63, v47
	v_exp_f32_e32 v64, v48
	v_add_f32_e32 v109, v61, v109
	v_add_f32_e32 v109, v62, v109
	v_add_f32_e32 v109, v63, v109
	v_add_f32_e32 v109, v64, v109
	v_mov_b32_e32 v65, v49
	s_mov_b64 s[46:47], 0
.LBB0_513:
	s_and_b64 vcc, exec, s[46:47]
	s_cbranch_vccz .LBB0_506
	s_nop 8
	v_cndmask_b32_e64 v34, v34, v208, s[36:37]
	v_exp_f32_e32 v50, v34
	v_mov_b32_e32 v34, v35
	v_mov_b32_e32 v35, v37
	v_cndmask_b32_e64 v35, v35, v208, s[8:9]
	v_exp_f32_e32 v53, v35
	v_mov_b32_e32 v35, v38
	v_cndmask_b32_e64 v35, v35, v208, s[10:11]
	v_exp_f32_e32 v54, v35
	v_mov_b32_e32 v35, v39
	v_cndmask_b32_e64 v35, v35, v208, s[12:13]
	v_exp_f32_e32 v55, v35
	v_mov_b32_e32 v35, v40
	v_cndmask_b32_e64 v35, v35, v208, s[14:15]
	v_exp_f32_e32 v56, v35
	v_mov_b32_e32 v35, v41
	v_cndmask_b32_e64 v34, v208, v34, s[4:5]
	v_cndmask_b32_e64 v35, v35, v208, s[16:17]
	v_exp_f32_e32 v51, v34
	v_mov_b32_e32 v34, v36
	v_exp_f32_e32 v57, v35
	v_mov_b32_e32 v35, v42
	v_cndmask_b32_e64 v34, v34, v208, s[6:7]
	v_cndmask_b32_e64 v35, v35, v208, s[18:19]
	v_exp_f32_e32 v52, v34
	v_exp_f32_e32 v58, v35
	v_mov_b32_e32 v35, v43
	v_cndmask_b32_e64 v35, v35, v208, s[20:21]
	v_add_f32_e32 v34, v108, v50
	v_exp_f32_e32 v59, v35
	v_mov_b32_e32 v35, v44
	v_add_f32_e32 v34, v51, v34
	v_cndmask_b32_e64 v35, v35, v208, s[22:23]
	v_add_f32_e32 v34, v52, v34
	v_exp_f32_e32 v60, v35
	v_mov_b32_e32 v35, v45
	v_add_f32_e32 v34, v53, v34
	v_cndmask_b32_e64 v35, v35, v208, s[24:25]
	v_add_f32_e32 v34, v54, v34
	v_exp_f32_e32 v61, v35
	v_mov_b32_e32 v35, v46
	v_add_f32_e32 v34, v55, v34
	v_cndmask_b32_e64 v35, v35, v208, s[26:27]
	v_add_f32_e32 v34, v56, v34
	v_exp_f32_e32 v62, v35
	v_mov_b32_e32 v35, v47
	v_add_f32_e32 v34, v57, v34
	v_cndmask_b32_e64 v35, v35, v208, s[28:29]
	v_add_f32_e32 v34, v58, v34
	v_exp_f32_e32 v63, v35
	v_mov_b32_e32 v35, v48
	v_add_f32_e32 v34, v59, v34
	v_cndmask_b32_e64 v35, v35, v208, s[30:31]
	v_add_f32_e32 v34, v60, v34
	v_exp_f32_e32 v64, v35
	v_add_f32_e32 v34, v61, v34
	v_add_f32_e32 v34, v62, v34
	v_add_f32_e32 v34, v63, v34
	v_add_f32_e32 v109, v64, v34
	v_mov_b32_e32 v34, v49
	v_cndmask_b32_e64 v65, v34, v208, s[34:35]
	s_branch .LBB0_506
